# combo4 + static s_setprio 1 for waves 4-7 in GEMM phases, per-segment priority flips removed
# baseline (speedup 1.0000x reference)
; #define PG8_STAGE(bufoff, gbase, voff) do { _Pragma("unroll") for (int _i = 0; _i < 2; ++_i) \
;         __builtin_amdgcn_global_load_lds((const unsigned*)((const char*)(gbase) + (voff)[_i]), (PG8_LAS unsigned*)(lds + (bufoff) + ldsw + _i * 8192), 16, 0, 0); } while (0)
; #define PG8_WAIT_V(n) asm volatile("s_waitcnt vmcnt(" #n ")" ::: "memory")
; #define PG8_BAR __builtin_amdgcn_s_barrier()
; template <class Epi, class Sched, bool ALIGN_EPI = false, bool SP2 = false>
; __device__ __forceinline__ void gemm_phase(PG8_LAS unsigned char* lds, const Gemm g, const Sched& S, const Epi& E) {
;     int tid_ = threadIdx.x; asm volatile("" : "+v"(tid_));
;     const int tid = tid_, wid = __builtin_amdgcn_readfirstlane(tid >> 6), lane = tid & 63, wr = wid >> 2, wc = wid & 3, fr = lane & 15, fq = lane >> 4;
;     const int K = g.K, nt = K / BK;
;     unsigned voffA[2], voffB[2];
; #pragma unroll
;     for (int i = 0; i < 2; ++i) { int R, C; stage_rc(tid * 16 + i * 8192, R, C); const int Rb = Epi::PERM ? ((R & ~31) + perm32(R & 31)) : R;
;         voffA[i] = (unsigned)(R * g.lda + C) * 2u; voffB[i] = (unsigned)(Rb * g.ldb + C) * 2u; }
;     ...
;     const char* cA = (const char*)g.A + (size_t)cur.g * g.gsA * 2 + (size_t)cur.pm * tstepA; const char* cB = (const char*)g.Bt + (size_t)cur.g * g.gsB * 2 + (size_t)cur.pn * tstepB;
;     S.a_ready(cur);
;     if constexpr (SP2) {
;         PG8_STAGE(PG8_SB(0, 0), cB, voffB); PG8_STAGE(PG8_SB(0, 1), cB + hstepB, voffB); PG8_STAGE(PG8_SA(0, 0), cA, voffA); PG8_STAGE(PG8_SA(0, 1), cA + hstepA, voffA);
;         if (wr == 1) PG8_BAR;
;         PG8_WAIT_V(2); PG8_BAR;
.LBB0_187:
	s_cmp_lt_i32 s80, 2
	s_cselect_b64 s[0:1], -1, 0
	s_cmp_gt_i32 s81, 1
	s_cselect_b64 s[2:3], -1, 0
	s_and_b64 s[0:1], s[0:1], s[2:3]
	s_andn2_b64 vcc, exec, s[0:1]
	s_cbranch_vccnz .LBB0_266
	v_readfirstlane_b32 s98, v0
	s_lshr_b32 s98, s98, 8
	s_cmp_eq_u32 s98, 1
	s_cbranch_scc0 .Lsp_skip1
	s_setprio 1
.Lsp_skip1:
	v_mov_b32_e32 v13, v0
	s_cmpk_gt_i32 s96, 0x4ff
	v_readfirstlane_b32 s2, v13
	s_cbranch_scc1 .LBB0_212
	v_lshlrev_b32_e32 v1, 4, v13
	v_add_u32_e32 v2, 0x2000, v1
	v_ashrrev_i32_e32 v3, 31, v2
	v_lshrrev_b32_e32 v3, 22, v3
	v_add_u32_e32 v3, v2, v3
	v_ashrrev_i32_e32 v10, 10, v3
	v_mul_i32_i24_e32 v3, 0x400, v10
	v_sub_u32_e32 v2, v2, v3
	v_lshrrev_b32_e32 v3, 4, v2
	v_bitop3_b32 v2, v3, v2, 32 bitop3:0x6c
	v_ashrrev_i32_e32 v3, 31, v2
	v_lshrrev_b32_e32 v3, 26, v3
	v_add_u32_e32 v3, v2, v3
	v_lshlrev_b32_e32 v4, 3, v10
	v_ashrrev_i32_e32 v11, 6, v3
	v_and_b32_e32 v4, -16, v4
	v_add_u32_e32 v4, v11, v4
	v_and_b32_e32 v5, 3, v11
	s_mov_b32 s4, 0x1fffe0
	v_lshrrev_b32_e32 v6, 2, v4
	v_lshlrev_b32_e32 v7, 1, v4
	v_and_b32_e32 v3, 0xc0, v3
	v_and_or_b32 v5, v4, s4, v5
	v_and_b32_e32 v6, 4, v6
	v_and_b32_e32 v7, 24, v7
	v_sub_u32_e32 v2, v2, v3
	v_mov_b32_e32 v3, 1
	v_or3_b32 v5, v5, v6, v7
	v_lshlrev_b32_e32 v6, 5, v10
	v_ashrrev_i16_sdwa v2, v3, sext(v2) dst_sel:DWORD dst_unused:UNUSED_PAD src0_sel:DWORD src1_sel:BYTE_0
	v_and_b32_e32 v6, 32, v6
	v_bfe_i32 v12, v2, 0, 16
	v_add_lshl_u32 v2, v6, v12, 1
	v_lshl_add_u32 v130, v5, 11, v2
	v_lshl_add_u32 v132, v4, 11, v2
	v_bfe_i32 v2, v13, 27, 1
	v_lshrrev_b32_e32 v2, 22, v2
	v_add_u32_e32 v2, v1, v2
	v_and_b32_e32 v2, 0xfffffc00, v2
	v_sub_u32_e32 v1, v1, v2
	v_lshrrev_b32_e32 v2, 4, v1
	v_ashrrev_i32_e32 v4, 31, v13
	v_bitop3_b32 v1, v2, v1, 32 bitop3:0x6c
	v_lshrrev_b32_e32 v4, 26, v4
	v_ashrrev_i32_e32 v2, 31, v1
	v_add_u32_e32 v4, v13, v4
	s_add_u32 s3, s78, 0x7c00000
	v_lshrrev_b32_e32 v2, 26, v2
	v_ashrrev_i32_e32 v15, 6, v4
	s_addc_u32 s34, s79, 0
	v_add_u32_e32 v2, v1, v2
	v_lshlrev_b32_e32 v4, 3, v15
	s_add_u32 s35, s78, 0x2000000
	v_ashrrev_i32_e32 v14, 6, v2
	v_and_b32_e32 v4, -16, v4
	s_addc_u32 s36, s79, 0
	v_add_u32_e32 v4, v14, v4
	v_and_b32_e32 v5, 3, v14
	s_ashr_i32 s38, s96, 31
	v_and_or_b32 v5, v4, s4, v5
	s_lshr_b32 s4, s38, 29
	s_add_i32 s4, s96, s4
	s_ashr_i32 s1, s2, 6
	s_ashr_i32 s5, s4, 3
	s_and_b32 s4, s4, -8
	s_ashr_i32 s0, s2, 8
	s_lshl_b32 s37, s1, 10
	s_sub_i32 s4, s96, s4
	s_cmp_lt_i32 s4, 0
	s_movk_i32 s39, 0xa1
	s_cselect_b32 s6, s39, 0xa0
	s_mul_i32 s4, s4, s6
	s_add_i32 s4, s4, s5
	s_mul_hi_i32 s5, s4, 0x66666667
	s_lshr_b32 s6, s5, 31
	s_ashr_i32 s5, s5, 4
	s_add_i32 s5, s5, s6
	s_lshl_b32 s7, s5, 2
	s_mul_i32 s5, s5, 40
	s_sub_i32 s4, s4, s5
	s_bfe_i32 s5, s4, 0x80000
	s_bfe_u32 s5, s5, 0x2000d
	s_add_i32 s5, s4, s5
	s_bfe_i32 s6, s5, 0x80000
	s_and_b32 s5, s5, 0xfc
	s_sub_i32 s4, s4, s5
	s_sext_i32_i16 s6, s6
	s_sext_i32_i8 s4, s4
	v_lshrrev_b32_e32 v6, 2, v4
	v_lshlrev_b32_e32 v7, 1, v4
	v_and_b32_e32 v2, 0xc0, v2
	s_lshr_b32 s6, s6, 2
	s_add_i32 s4, s7, s4
	v_and_b32_e32 v6, 4, v6
	v_and_b32_e32 v7, 24, v7
	v_sub_u32_e32 v1, v1, v2
	s_ashr_i32 s5, s4, 31
	s_bfe_i64 s[10:11], s[6:7], 0x100000
	v_or3_b32 v5, v5, v6, v7
	v_lshlrev_b32_e32 v6, 5, v15
	v_ashrrev_i16_sdwa v1, v3, sext(v1) dst_sel:DWORD dst_unused:UNUSED_PAD src0_sel:DWORD src1_sel:BYTE_0
	s_lshl_b64 s[8:9], s[4:5], 19
	s_lshl_b64 s[10:11], s[10:11], 19
	v_and_b32_e32 v6, 32, v6
	v_bfe_i32 v16, v1, 0, 16
	s_add_u32 s28, s35, s10
	v_add_lshl_u32 v1, v6, v16, 1
	s_addc_u32 s29, s36, s11
	s_add_i32 s40, s37, 0
	v_lshl_add_u32 v134, v5, 11, v1
	s_add_i32 m0, s40, 0x10000
	v_lshl_add_u32 v136, v4, 11, v1
	global_load_lds_dwordx4 v134, s[28:29]
	s_add_i32 m0, s40, 0x12000
	s_add_u32 s10, s28, 0x40000
	global_load_lds_dwordx4 v130, s[28:29]
	s_addc_u32 s11, s29, 0
	s_add_i32 m0, s40, 0x14000
	v_mov_b32_e32 v139, 0
	global_load_lds_dwordx4 v134, s[10:11]
	s_add_i32 m0, s40, 0x16000
	s_add_u32 s26, s3, s8
	s_addc_u32 s27, s34, s9
	s_add_i32 s41, s40, 0x2000
	global_load_lds_dwordx4 v130, s[10:11]
	s_mov_b32 m0, s40
	s_add_u32 s8, s26, 0x40000
	global_load_lds_dwordx4 v136, s[26:27]
	s_mov_b32 m0, s41
	s_addc_u32 s9, s27, 0
	s_add_i32 s42, s40, 0x4000
	global_load_lds_dwordx4 v132, s[26:27]
	s_mov_b32 m0, s42
	s_add_i32 s43, s40, 0x6000
	global_load_lds_dwordx4 v136, s[8:9]
	s_mov_b32 m0, s43
	v_mov_b32_e32 v135, v139
	global_load_lds_dwordx4 v132, s[8:9]
	v_mov_b32_e32 v131, v139
	v_mov_b32_e32 v137, v139
	v_mov_b32_e32 v133, v139
	s_cmp_eq_u32 s0, 1
	s_movk_i32 s44, 0x2000
	s_mov_b32 s45, 0
	v_lshl_add_u64 v[8:9], s[28:29], 0, v[134:135]
	v_lshl_add_u64 v[6:7], s[28:29], 0, v[130:131]
	v_lshl_add_u64 v[2:3], s[26:27], 0, v[136:137]
	s_cselect_b64 s[8:9], -1, 0
	s_cmp_lg_u32 s0, 1
	v_lshl_add_u64 v[4:5], s[26:27], 0, v[132:133]
	s_cbranch_scc1 .LBB0_191
	s_barrier

; #define SEAM(k) do { if (IN((k) + 1)) grid.sync(); } while (0)
; #define SEAM(k) do { if (hi > (k) + 1) { if (lo > hi) grid.sync(); xcd_barrier(bar); } } while (0)
; __global__ void __launch_bounds__(NTHR, 2) hybrid_fwd(Args args) {
;     ...
;     if (IN(2)) { BODY2; if (PROBE_ID == 102) BODY2; SEAM(2); }
.LBB0_266:
	s_setprio 0
	s_cmp_lt_i32 s80, 3
	s_cselect_b64 s[0:1], -1, 0
	s_cmp_gt_i32 s81, 2
	s_cselect_b64 s[2:3], -1, 0
	s_and_b64 s[0:1], s[0:1], s[2:3]
	s_andn2_b64 vcc, exec, s[0:1]
	s_cbranch_vccnz .LBB0_346
	s_and_b32 s0, s82, 7
	s_cmp_lg_u32 s0, 0
	s_mov_b32 s0, s96
	s_cbranch_scc1 .LBB0_269
	s_and_b32 s0, s96, 7
	s_lshr_b32 s1, s82, 3
	s_mul_i32 s0, s1, s0
	s_lshr_b32 s1, s96, 3
	s_add_i32 s0, s0, s1

; #define SEAM(k) do { if (IN((k) + 1)) grid.sync(); } while (0)
; #define SEAM(k) do { if (hi > (k) + 1) { if (lo > hi) grid.sync(); xcd_barrier(bar); } } while (0)
; __global__ void __launch_bounds__(NTHR, 2) hybrid_fwd(Args args) {
;     ...
;     if (IN(6)) { BODY6; if (PROBE_ID == 106) BODY6; SEAM(6); }
.LBB0_584:
	s_cmp_lt_i32 s80, 7
	s_cselect_b64 s[0:1], -1, 0
	s_cmp_gt_i32 s81, 6
	s_cselect_b64 s[2:3], -1, 0
	s_and_b64 s[0:1], s[0:1], s[2:3]
	s_andn2_b64 vcc, exec, s[0:1]
	s_cbranch_vccnz .LBB0_681
	v_readfirstlane_b32 s98, v0
	s_lshr_b32 s98, s98, 8
	s_cmp_eq_u32 s98, 1
	s_cbranch_scc0 .Lsp_skip6
	s_setprio 1

; #define PG8_STAGE(bufoff, gbase, voff) do { _Pragma("unroll") for (int _i = 0; _i < 2; ++_i) \
;         __builtin_amdgcn_global_load_lds((const unsigned*)((const char*)(gbase) + (voff)[_i]), (PG8_LAS unsigned*)(lds + (bufoff) + ldsw + _i * 8192), 16, 0, 0); } while (0)
; #define PG8_WAIT_V(n) asm volatile("s_waitcnt vmcnt(" #n ")" ::: "memory")
; #define PG8_BAR __builtin_amdgcn_s_barrier()
; template <class Epi, class Sched, bool ALIGN_EPI = false, bool SP2 = false>
; __device__ __forceinline__ void gemm_phase(PG8_LAS unsigned char* lds, const Gemm g, const Sched& S, const Epi& E) {
;     int tid_ = threadIdx.x; asm volatile("" : "+v"(tid_));
;     const int tid = tid_, wid = __builtin_amdgcn_readfirstlane(tid >> 6), lane = tid & 63, wr = wid >> 2, wc = wid & 3, fr = lane & 15, fq = lane >> 4;
;     const int K = g.K, nt = K / BK;
;     unsigned voffA[2], voffB[2];
; #pragma unroll
;     for (int i = 0; i < 2; ++i) { int R, C; stage_rc(tid * 16 + i * 8192, R, C); const int Rb = Epi::PERM ? ((R & ~31) + perm32(R & 31)) : R;
;         voffA[i] = (unsigned)(R * g.lda + C) * 2u; voffB[i] = (unsigned)(Rb * g.ldb + C) * 2u; }
;     ...
;     const char* cA = (const char*)g.A + (size_t)cur.g * g.gsA * 2 + (size_t)cur.pm * tstepA; const char* cB = (const char*)g.Bt + (size_t)cur.g * g.gsB * 2 + (size_t)cur.pn * tstepB;
;     S.a_ready(cur);
;     if constexpr (SP2) {
;         PG8_STAGE(PG8_SB(0, 0), cB, voffB); PG8_STAGE(PG8_SB(0, 1), cB + hstepB, voffB); PG8_STAGE(PG8_SA(0, 0), cA, voffA); PG8_STAGE(PG8_SA(0, 1), cA + hstepA, voffA);
;         if (wr == 1) PG8_BAR;
;         PG8_WAIT_V(2); PG8_BAR;
.LBB0_681:
	s_setprio 0
	s_cmp_lt_i32 s80, 8
	s_cselect_b64 s[0:1], -1, 0
	s_cmp_gt_i32 s81, 7
	s_cselect_b64 s[2:3], -1, 0
	s_and_b64 s[0:1], s[0:1], s[2:3]
	s_andn2_b64 vcc, exec, s[0:1]
	s_cbranch_vccnz .LBB0_752
	v_readfirstlane_b32 s98, v0
	s_lshr_b32 s98, s98, 8
	s_cmp_eq_u32 s98, 1
	s_cbranch_scc0 .Lsp_skip7
	s_setprio 1
.Lsp_skip7:
	v_mov_b32_e32 v12, v0
	s_cmpk_gt_i32 s96, 0xaff
	v_readfirstlane_b32 s7, v12
	s_cbranch_scc1 .LBB0_698
	v_lshlrev_b32_e32 v1, 4, v12
	v_add_u32_e32 v2, 0x2000, v1
	s_waitcnt lgkmcnt(0)
	v_ashrrev_i32_e32 v3, 31, v2
	v_lshrrev_b32_e32 v3, 22, v3
	v_add_u32_e32 v3, v2, v3
	v_ashrrev_i32_e32 v10, 10, v3
	v_mul_i32_i24_e32 v3, 0x400, v10
	v_sub_u32_e32 v2, v2, v3
	v_lshrrev_b32_e32 v3, 4, v2
	v_bitop3_b32 v2, v3, v2, 32 bitop3:0x6c
	v_ashrrev_i32_e32 v3, 31, v2
	v_lshrrev_b32_e32 v3, 26, v3
	v_add_u32_e32 v3, v2, v3
	v_lshlrev_b32_e32 v4, 3, v10
	v_ashrrev_i32_e32 v11, 6, v3
	v_and_b32_e32 v4, -16, v4
	v_add_u32_e32 v4, v11, v4
	v_and_b32_e32 v5, 3, v11
	s_mov_b32 s4, 0x1fffe0
	v_lshrrev_b32_e32 v6, 2, v4
	v_lshlrev_b32_e32 v7, 1, v4
	v_and_b32_e32 v3, 0xc0, v3
	v_and_or_b32 v5, v4, s4, v5
	v_and_b32_e32 v6, 4, v6
	v_and_b32_e32 v7, 24, v7
	v_sub_u32_e32 v2, v2, v3
	v_mov_b32_e32 v3, 1
	v_or3_b32 v5, v5, v6, v7
	v_lshlrev_b32_e32 v6, 5, v10
	v_ashrrev_i16_sdwa v2, v3, sext(v2) dst_sel:DWORD dst_unused:UNUSED_PAD src0_sel:DWORD src1_sel:BYTE_0
	v_and_b32_e32 v6, 32, v6
	v_bfe_i32 v13, v2, 0, 16
	v_add_lshl_u32 v2, v6, v13, 1
	v_lshl_add_u32 v130, v5, 11, v2
	v_lshl_add_u32 v132, v4, 11, v2
	v_bfe_i32 v2, v12, 27, 1
	v_lshrrev_b32_e32 v2, 22, v2
	v_add_u32_e32 v2, v1, v2
	v_and_b32_e32 v2, 0xfffffc00, v2
	v_sub_u32_e32 v1, v1, v2
	v_lshrrev_b32_e32 v2, 4, v1
	v_ashrrev_i32_e32 v4, 31, v12
	v_bitop3_b32 v1, v2, v1, 32 bitop3:0x6c
	v_lshrrev_b32_e32 v4, 26, v4
	v_ashrrev_i32_e32 v2, 31, v1
	v_add_u32_e32 v4, v12, v4
	s_add_u32 s0, s78, 0x7c00000
	v_lshrrev_b32_e32 v2, 26, v2
	v_ashrrev_i32_e32 v15, 6, v4
	s_addc_u32 s1, s79, 0
	v_add_u32_e32 v2, v1, v2
	v_lshlrev_b32_e32 v4, 3, v15
	s_add_u32 s2, s78, 0x3000000
	v_ashrrev_i32_e32 v14, 6, v2
	v_and_b32_e32 v4, -16, v4
	s_addc_u32 s3, s79, 0
	v_add_u32_e32 v4, v14, v4
	v_and_b32_e32 v5, 3, v14
	s_ashr_i32 s31, s96, 31
	v_and_or_b32 v5, v4, s4, v5
	s_lshr_b32 s4, s31, 29
	s_add_i32 s4, s96, s4
	s_ashr_i32 s10, s7, 6
	s_ashr_i32 s5, s4, 3
	s_and_b32 s4, s4, -8
	s_ashr_i32 s12, s7, 8
	s_lshl_b32 s30, s10, 10
	s_sub_i32 s4, s96, s4
	s_cmp_lt_i32 s4, 0
	s_movk_i32 s33, 0x161
	s_cselect_b32 s6, s33, 0x160
	s_mul_i32 s4, s4, s6
	s_add_i32 s4, s4, s5
	s_mul_hi_i32 s5, s4, 0x2e8ba2e9
	s_lshr_b32 s6, s5, 31
	s_ashr_i32 s5, s5, 4
	s_add_i32 s5, s5, s6
	s_lshl_b32 s8, s5, 2
	s_mulk_i32 s5, 0x58
	s_sub_i32 s4, s4, s5
	s_bfe_i32 s5, s4, 0x80000
	s_bfe_u32 s5, s5, 0x2000d
	s_add_i32 s5, s4, s5
	s_bfe_i32 s6, s5, 0x80000
	s_and_b32 s5, s5, 0xfc
	s_sub_i32 s4, s4, s5
	s_sext_i32_i16 s6, s6
	s_sext_i32_i8 s4, s4
	v_lshrrev_b32_e32 v6, 2, v4
	v_lshlrev_b32_e32 v7, 1, v4
	v_and_b32_e32 v2, 0xc0, v2
	s_lshr_b32 s6, s6, 2
	s_add_i32 s22, s8, s4
	v_and_b32_e32 v6, 4, v6
	v_and_b32_e32 v7, 24, v7
	v_sub_u32_e32 v1, v1, v2
	s_ashr_i32 s23, s22, 31
	s_bfe_i64 s[8:9], s[6:7], 0x100000
	v_or3_b32 v5, v5, v6, v7
	v_lshlrev_b32_e32 v6, 5, v15
	v_ashrrev_i16_sdwa v1, v3, sext(v1) dst_sel:DWORD dst_unused:UNUSED_PAD src0_sel:DWORD src1_sel:BYTE_0
	s_lshl_b64 s[4:5], s[22:23], 19
	s_lshl_b64 s[8:9], s[8:9], 19
	v_and_b32_e32 v6, 32, v6
	v_bfe_i32 v16, v1, 0, 16
	s_add_u32 s26, s2, s8
	v_add_lshl_u32 v1, v6, v16, 1
	s_addc_u32 s27, s3, s9
	s_add_i32 s23, s30, 0
	v_lshl_add_u32 v134, v5, 11, v1
	s_add_i32 m0, s23, 0x10000
	v_lshl_add_u32 v136, v4, 11, v1
	global_load_lds_dwordx4 v134, s[26:27]
	s_add_i32 m0, s23, 0x12000
	s_add_u32 s8, s26, 0x40000
	global_load_lds_dwordx4 v130, s[26:27]
	s_addc_u32 s9, s27, 0
	s_add_i32 m0, s23, 0x14000
	v_mov_b32_e32 v135, 0
	global_load_lds_dwordx4 v134, s[8:9]
	s_add_i32 m0, s23, 0x16000
	s_add_u32 s24, s0, s4
	s_addc_u32 s25, s1, s5
	s_add_i32 s34, s23, 0x2000
	global_load_lds_dwordx4 v130, s[8:9]
	s_mov_b32 m0, s23
	s_add_u32 s4, s24, 0x40000
	global_load_lds_dwordx4 v136, s[24:25]
	s_mov_b32 m0, s34
	s_addc_u32 s5, s25, 0
	s_add_i32 s35, s23, 0x4000
	global_load_lds_dwordx4 v132, s[24:25]
	s_mov_b32 m0, s35
	s_add_i32 s36, s23, 0x6000
	global_load_lds_dwordx4 v136, s[4:5]
	s_mov_b32 m0, s36
	v_mov_b32_e32 v131, v135
	global_load_lds_dwordx4 v132, s[4:5]
	v_mov_b32_e32 v137, v135
	v_mov_b32_e32 v133, v135
	s_cmp_eq_u32 s12, 1
	s_mov_b32 s37, 0
	v_lshl_add_u64 v[8:9], s[26:27], 0, v[134:135]
	v_lshl_add_u64 v[6:7], s[26:27], 0, v[130:131]
	v_lshl_add_u64 v[2:3], s[24:25], 0, v[136:137]
	s_cselect_b64 s[4:5], -1, 0
	s_cmp_lg_u32 s12, 1
	v_lshl_add_u64 v[4:5], s[24:25], 0, v[132:133]
	s_cbranch_scc1 .LBB0_685
	s_barrier

.LBB0_752:
	s_setprio 0
	s_cmp_lt_i32 s80, 9
	s_cselect_b64 s[0:1], -1, 0
	s_cmp_gt_i32 s81, 8
	s_cselect_b64 s[2:3], -1, 0
	s_and_b64 s[0:1], s[0:1], s[2:3]
	s_andn2_b64 vcc, exec, s[0:1]
	s_cbranch_vccnz .LBB0_882
	v_readfirstlane_b32 s98, v0
	s_lshr_b32 s98, s98, 8
	s_cmp_eq_u32 s98, 1
	s_cbranch_scc0 .Lsp_skip8
	s_setprio 1
.Lsp_skip8:
	v_mov_b32_e32 v10, v0
	s_cmpk_lt_i32 s96, 0x200
	s_waitcnt lgkmcnt(0)
	s_cselect_b64 s[4:5], -1, 0
	s_cmpk_gt_i32 s96, 0x1ff
	v_readfirstlane_b32 s8, v10
	s_cbranch_scc1 .LBB0_759
	s_ashr_i32 s0, s96, 31
	s_lshr_b32 s0, s0, 29
	s_add_i32 s0, s96, s0
	s_and_b32 s1, s0, -8
	s_sub_i32 s1, s96, s1
	s_cmp_gt_i32 s1, -1
	s_cbranch_scc0 .LBB0_756
	s_lshl_b32 s2, s1, 6
	s_cbranch_execz .LBB0_757
	s_branch .LBB0_758

.LBB0_882:
	s_setprio 0
	s_cmp_lt_i32 s80, 10
	s_cselect_b64 s[0:1], -1, 0
	s_cmp_gt_i32 s81, 9
	s_cselect_b64 s[2:3], -1, 0
	s_and_b64 s[0:1], s[0:1], s[2:3]
	s_andn2_b64 vcc, exec, s[0:1]
	s_cbranch_vccnz .LBB0_979
	v_readfirstlane_b32 s98, v0
	s_lshr_b32 s98, s98, 8
	s_cmp_eq_u32 s98, 1
	s_cbranch_scc0 .Lsp_skip9
	s_setprio 1

; #define PG8_STAGE(bufoff, gbase, voff) do { _Pragma("unroll") for (int _i = 0; _i < 2; ++_i) \
;         __builtin_amdgcn_global_load_lds((const unsigned*)((const char*)(gbase) + (voff)[_i]), (PG8_LAS unsigned*)(lds + (bufoff) + ldsw + _i * 8192), 16, 0, 0); } while (0)
; #define PG8_BAR __builtin_amdgcn_s_barrier()
; template <class Epi, class Sched, bool ALIGN_EPI = false, bool SP2 = false>
; __device__ __forceinline__ void gemm_phase(PG8_LAS unsigned char* lds, const Gemm g, const Sched& S, const Epi& E) {
;     int tid_ = threadIdx.x; asm volatile("" : "+v"(tid_));
;     const int tid = tid_, wid = __builtin_amdgcn_readfirstlane(tid >> 6), lane = tid & 63, wr = wid >> 2, wc = wid & 3, fr = lane & 15, fq = lane >> 4;
;     const int K = g.K, nt = K / BK;
;     unsigned voffA[2], voffB[2];
; #pragma unroll
;     for (int i = 0; i < 2; ++i) { int R, C; stage_rc(tid * 16 + i * 8192, R, C); const int Rb = Epi::PERM ? ((R & ~31) + perm32(R & 31)) : R;
;         voffA[i] = (unsigned)(R * g.lda + C) * 2u; voffB[i] = (unsigned)(Rb * g.ldb + C) * 2u; }
;     const size_t kstep = (size_t)(BK * 2);
;     const size_t hstepA = (size_t)HALF * g.lda * 2, hstepB = (size_t)HALF * g.ldb * 2;
;     const size_t tstepA = 2 * hstepA, tstepB = 2 * hstepB;
;     const unsigned ldsw = (unsigned)wid * 1024u;
;     const int aoff = lds_byte(wr * 64 + fr, fq * 8), boff = lds_byte(wc * 32 + fr, fq * 8);
;     ...
;     Unit cur, nxt; int ui = 0;
;     if (!S.next(0, cur)) return;
;     f32x4 acc[2][2][4][2];
; #pragma unroll
;     for (int a = 0; a < 2; ++a)
; #pragma unroll
;         for (int b = 0; b < 2; ++b)
; #pragma unroll
;             for (int m = 0; m < 4; ++m)
; #pragma unroll
;                 for (int n = 0; n < 2; ++n) acc[a][b][m][n] = (f32x4){0.f, 0.f, 0.f, 0.f};
;     bf16x8 At[4][2], B0[2][2], B1[2][2];
;     const char* cA = (const char*)g.A + (size_t)cur.g * g.gsA * 2 + (size_t)cur.pm * tstepA; const char* cB = (const char*)g.Bt + (size_t)cur.g * g.gsB * 2 + (size_t)cur.pn * tstepB;
;     S.a_ready(cur);
;     if constexpr (SP2) {
;         PG8_STAGE(PG8_SB(0, 0), cB, voffB); PG8_STAGE(PG8_SB(0, 1), cB + hstepB, voffB); PG8_STAGE(PG8_SA(0, 0), cA, voffA); PG8_STAGE(PG8_SA(0, 1), cA + hstepA, voffA);
;         if (wr == 1) PG8_BAR;
.LBB0_979:
	s_setprio 0
	s_cmp_lt_i32 s80, 11
	s_cselect_b64 s[0:1], -1, 0
	s_cmp_gt_i32 s81, 10
	s_cselect_b64 s[2:3], -1, 0
	s_and_b64 s[0:1], s[0:1], s[2:3]
	s_andn2_b64 vcc, exec, s[0:1]
	s_cbranch_vccnz .LBB0_1054
	v_readfirstlane_b32 s98, v0
	s_lshr_b32 s98, s98, 8
	s_cmp_eq_u32 s98, 1
	s_cbranch_scc0 .Lsp_skip10
	s_setprio 1
.Lsp_skip10:
	v_mov_b32_e32 v12, v0
	s_cmpk_gt_i32 s96, 0x5ff
	v_readfirstlane_b32 s1, v12
	s_cbranch_scc1 .LBB0_1000
	v_lshlrev_b32_e32 v1, 4, v12
	v_add_u32_e32 v2, 0x2000, v1
	s_waitcnt lgkmcnt(0)
	v_ashrrev_i32_e32 v3, 31, v2
	v_lshrrev_b32_e32 v3, 22, v3
	v_add_u32_e32 v3, v2, v3
	v_ashrrev_i32_e32 v10, 10, v3
	v_mul_i32_i24_e32 v3, 0x400, v10
	v_sub_u32_e32 v2, v2, v3
	v_lshrrev_b32_e32 v3, 4, v2
	v_bitop3_b32 v2, v3, v2, 32 bitop3:0x6c
	v_ashrrev_i32_e32 v3, 31, v2
	v_lshrrev_b32_e32 v3, 26, v3
	v_add_u32_e32 v3, v2, v3
	v_lshlrev_b32_e32 v4, 3, v10
	v_ashrrev_i32_e32 v11, 6, v3
	v_and_b32_e32 v4, -16, v4
	v_add_u32_e32 v4, v11, v4
	v_and_b32_e32 v5, 3, v11
	s_mov_b32 s2, 0x1fffe0
	v_lshrrev_b32_e32 v6, 2, v4
	v_lshlrev_b32_e32 v7, 1, v4
	v_and_b32_e32 v3, 0xc0, v3
	v_and_or_b32 v5, v4, s2, v5
	v_and_b32_e32 v6, 4, v6
	v_and_b32_e32 v7, 24, v7
	v_sub_u32_e32 v2, v2, v3
	v_mov_b32_e32 v3, 1
	v_or3_b32 v5, v5, v6, v7
	v_lshlrev_b32_e32 v6, 5, v10
	v_ashrrev_i16_sdwa v2, v3, sext(v2) dst_sel:DWORD dst_unused:UNUSED_PAD src0_sel:DWORD src1_sel:BYTE_0
	v_and_b32_e32 v6, 32, v6
	v_bfe_i32 v13, v2, 0, 16
	v_add_lshl_u32 v2, v6, v13, 1
	v_lshl_add_u32 v130, v5, 11, v2
	v_lshl_add_u32 v132, v4, 11, v2
	v_bfe_i32 v2, v12, 27, 1
	v_lshrrev_b32_e32 v2, 22, v2
	v_add_u32_e32 v2, v1, v2
	v_and_b32_e32 v2, 0xfffffc00, v2
	v_sub_u32_e32 v1, v1, v2
	v_lshrrev_b32_e32 v2, 4, v1
	v_ashrrev_i32_e32 v4, 31, v12
	v_bitop3_b32 v1, v2, v1, 32 bitop3:0x6c
	v_lshrrev_b32_e32 v4, 26, v4
	v_ashrrev_i32_e32 v2, 31, v1
	v_add_u32_e32 v4, v12, v4
	s_add_u32 s3, s78, 0xfc00000
	v_lshrrev_b32_e32 v2, 26, v2
	v_ashrrev_i32_e32 v15, 6, v4
	s_addc_u32 s30, s79, 0
	v_add_u32_e32 v2, v1, v2
	v_lshlrev_b32_e32 v4, 3, v15
	s_add_u32 s31, s78, 0x2800000
	v_ashrrev_i32_e32 v14, 6, v2
	v_and_b32_e32 v4, -16, v4
	s_addc_u32 s34, s79, 0
	v_add_u32_e32 v4, v14, v4
	v_and_b32_e32 v5, 3, v14
	s_ashr_i32 s36, s96, 31
	v_and_or_b32 v5, v4, s2, v5
	s_lshr_b32 s2, s36, 29
	s_add_i32 s2, s96, s2
	s_ashr_i32 s7, s1, 6
	s_ashr_i32 s4, s2, 3
	s_and_b32 s2, s2, -8
	s_ashr_i32 s0, s1, 8
	s_lshl_b32 s35, s7, 10
	s_sub_i32 s2, s96, s2
	s_cmp_lt_i32 s2, 0
	s_movk_i32 s37, 0xc1
	s_cselect_b32 s5, s37, 0xc0
	s_mul_i32 s2, s2, s5
	s_add_i32 s2, s2, s4
	s_mul_hi_i32 s4, s2, 0x2aaaaaab
	s_lshr_b32 s5, s4, 31
	s_ashr_i32 s4, s4, 3
	s_add_i32 s4, s4, s5
	s_lshl_b32 s5, s4, 2
	s_mul_i32 s4, s4, 48
	s_sub_i32 s2, s2, s4
	s_bfe_i32 s4, s2, 0x80000
	s_bfe_u32 s4, s4, 0x2000d
	s_add_i32 s4, s2, s4
	s_bfe_i32 s6, s4, 0x80000
	s_and_b32 s4, s4, 0xfc
	s_sub_i32 s2, s2, s4
	s_sext_i32_i16 s6, s6
	s_sext_i32_i8 s2, s2
	v_lshrrev_b32_e32 v6, 2, v4
	v_lshlrev_b32_e32 v7, 1, v4
	v_and_b32_e32 v2, 0xc0, v2
	s_lshr_b32 s6, s6, 2
	s_add_i32 s4, s5, s2
	v_and_b32_e32 v6, 4, v6
	v_and_b32_e32 v7, 24, v7
	v_sub_u32_e32 v1, v1, v2
	s_ashr_i32 s5, s4, 31
	s_bfe_i64 s[10:11], s[6:7], 0x100000
	v_or3_b32 v5, v5, v6, v7
	v_lshlrev_b32_e32 v6, 5, v15
	v_ashrrev_i16_sdwa v1, v3, sext(v1) dst_sel:DWORD dst_unused:UNUSED_PAD src0_sel:DWORD src1_sel:BYTE_0
	s_lshl_b64 s[8:9], s[4:5], 19
	s_lshl_b64 s[10:11], s[10:11], 19
	v_and_b32_e32 v6, 32, v6
	v_bfe_i32 v16, v1, 0, 16
	s_add_u32 s26, s31, s10
	v_add_lshl_u32 v1, v6, v16, 1
	s_addc_u32 s27, s34, s11
	s_add_i32 s38, s35, 0
	v_lshl_add_u32 v134, v5, 11, v1
	s_add_i32 m0, s38, 0x10000
	v_lshl_add_u32 v136, v4, 11, v1
	global_load_lds_dwordx4 v134, s[26:27]
	s_add_i32 m0, s38, 0x12000
	s_add_u32 s10, s26, 0x40000
	global_load_lds_dwordx4 v130, s[26:27]
	s_addc_u32 s11, s27, 0
	s_add_i32 m0, s38, 0x14000
	v_mov_b32_e32 v139, 0
	global_load_lds_dwordx4 v134, s[10:11]
	s_add_i32 m0, s38, 0x16000
	s_add_u32 s24, s3, s8
	s_addc_u32 s25, s30, s9
	s_add_i32 s39, s38, 0x2000
	global_load_lds_dwordx4 v130, s[10:11]
	s_mov_b32 m0, s38
	s_add_u32 s8, s24, 0x40000
	global_load_lds_dwordx4 v136, s[24:25]
	s_mov_b32 m0, s39
	s_addc_u32 s9, s25, 0
	s_add_i32 s40, s38, 0x4000
	global_load_lds_dwordx4 v132, s[24:25]
	s_mov_b32 m0, s40
	s_add_i32 s41, s38, 0x6000
	global_load_lds_dwordx4 v136, s[8:9]
	s_mov_b32 m0, s41
	v_mov_b32_e32 v135, v139
	global_load_lds_dwordx4 v132, s[8:9]
	v_mov_b32_e32 v131, v139
	v_mov_b32_e32 v137, v139
	v_mov_b32_e32 v133, v139
	s_cmp_eq_u32 s0, 1
	s_movk_i32 s42, 0x2000
	s_mov_b32 s43, 0
	v_lshl_add_u64 v[8:9], s[26:27], 0, v[134:135]
	v_lshl_add_u64 v[6:7], s[26:27], 0, v[130:131]
	v_lshl_add_u64 v[2:3], s[24:25], 0, v[136:137]
	s_cselect_b64 s[8:9], -1, 0
	s_cmp_lg_u32 s0, 1
	v_lshl_add_u64 v[4:5], s[24:25], 0, v[132:133]
	s_cbranch_scc1 .LBB0_983
	s_barrier

.LBB0_1054:
	s_setprio 0
	s_cmp_lt_i32 s80, 12
	s_cselect_b64 s[0:1], -1, 0
	s_cmp_gt_i32 s81, 11
	s_cselect_b64 s[2:3], -1, 0
	s_and_b64 s[0:1], s[0:1], s[2:3]
	s_andn2_b64 vcc, exec, s[0:1]
	s_cbranch_vccnz .LBB0_1446
	s_and_b32 s0, s82, 7
	s_cmp_lg_u32 s0, 0
	s_mov_b32 s50, s96
	s_cbranch_scc1 .LBB0_1057
	s_ashr_i32 s1, s96, 31
	s_lshr_b32 s1, s1, 29
	s_add_i32 s1, s96, s1
	s_and_b32 s2, s1, -8
	s_ashr_i32 s0, s82, 3
	s_sub_i32 s2, s96, s2
	s_mul_i32 s0, s0, s2
	s_ashr_i32 s1, s1, 3
	s_add_i32 s50, s0, s1

; #define SEAM(k) do { if (IN((k) + 1)) grid.sync(); } while (0)
; #define GEMM_STD(Aptr, Bptr, ldk, Ncols, EpiT, Eobj) do { pg8::Gemm g_{(const bf16*)(Aptr), (const bf16*)(Bptr), (ldk), (ldk), (ldk), 0, 0}; pg8::StaticOrder S_; S_.init(M, (Ncols), (int)gridDim.x, (int)blockIdx.x); \
;         pg8::gemm_phase<EpiT, pg8::StaticOrder, true, true>((LAS unsigned char*)lds, g_, S_, Eobj); } while (0)
; #define SEAM(k) do { if (hi > (k) + 1) { if (lo > hi) grid.sync(); xcd_barrier(bar); } } while (0)
; __global__ void __launch_bounds__(NTHR, 2) hybrid_fwd(Args args) {
;     ...
;     if (IN(13)) { EpiRes<false> E{WSB(WS_MIX), WSB(WS_MIX), SSQ(4)}; GEMM_STD(WSB(WS_PP), WSB(WS_WO), 1024, 1024, EpiRes<false>, E); SEAM(13); }
.LBB0_1446:
	s_cmp_lt_i32 s80, 14
	s_cselect_b64 s[0:1], -1, 0
	s_cmp_gt_i32 s81, 13
	s_cselect_b64 s[2:3], -1, 0
	s_and_b64 s[0:1], s[0:1], s[2:3]
	s_andn2_b64 vcc, exec, s[0:1]
	s_cbranch_vccnz .LBB0_1543
	v_readfirstlane_b32 s98, v0
	s_lshr_b32 s98, s98, 8
	s_cmp_eq_u32 s98, 1
	s_cbranch_scc0 .Lsp_skip13
	s_setprio 1

; #define PG8_STAGE(bufoff, gbase, voff) do { _Pragma("unroll") for (int _i = 0; _i < 2; ++_i) \
;         __builtin_amdgcn_global_load_lds((const unsigned*)((const char*)(gbase) + (voff)[_i]), (PG8_LAS unsigned*)(lds + (bufoff) + ldsw + _i * 8192), 16, 0, 0); } while (0)
; #define PG8_BAR __builtin_amdgcn_s_barrier()
; template <class Epi, class Sched, bool ALIGN_EPI = false, bool SP2 = false>
; __device__ __forceinline__ void gemm_phase(PG8_LAS unsigned char* lds, const Gemm g, const Sched& S, const Epi& E) {
;     int tid_ = threadIdx.x; asm volatile("" : "+v"(tid_));
;     const int tid = tid_, wid = __builtin_amdgcn_readfirstlane(tid >> 6), lane = tid & 63, wr = wid >> 2, wc = wid & 3, fr = lane & 15, fq = lane >> 4;
;     const int K = g.K, nt = K / BK;
;     unsigned voffA[2], voffB[2];
; #pragma unroll
;     for (int i = 0; i < 2; ++i) { int R, C; stage_rc(tid * 16 + i * 8192, R, C); const int Rb = Epi::PERM ? ((R & ~31) + perm32(R & 31)) : R;
;         voffA[i] = (unsigned)(R * g.lda + C) * 2u; voffB[i] = (unsigned)(Rb * g.ldb + C) * 2u; }
;     const size_t kstep = (size_t)(BK * 2);
;     const size_t hstepA = (size_t)HALF * g.lda * 2, hstepB = (size_t)HALF * g.ldb * 2;
;     const size_t tstepA = 2 * hstepA, tstepB = 2 * hstepB;
;     const unsigned ldsw = (unsigned)wid * 1024u;
;     const int aoff = lds_byte(wr * 64 + fr, fq * 8), boff = lds_byte(wc * 32 + fr, fq * 8);
;     ...
;     Unit cur, nxt; int ui = 0;
;     if (!S.next(0, cur)) return;
;     f32x4 acc[2][2][4][2];
; #pragma unroll
;     for (int a = 0; a < 2; ++a)
; #pragma unroll
;         for (int b = 0; b < 2; ++b)
; #pragma unroll
;             for (int m = 0; m < 4; ++m)
; #pragma unroll
;                 for (int n = 0; n < 2; ++n) acc[a][b][m][n] = (f32x4){0.f, 0.f, 0.f, 0.f};
;     bf16x8 At[4][2], B0[2][2], B1[2][2];
;     const char* cA = (const char*)g.A + (size_t)cur.g * g.gsA * 2 + (size_t)cur.pm * tstepA; const char* cB = (const char*)g.Bt + (size_t)cur.g * g.gsB * 2 + (size_t)cur.pn * tstepB;
;     S.a_ready(cur);
;     if constexpr (SP2) {
;         PG8_STAGE(PG8_SB(0, 0), cB, voffB); PG8_STAGE(PG8_SB(0, 1), cB + hstepB, voffB); PG8_STAGE(PG8_SA(0, 0), cA, voffA); PG8_STAGE(PG8_SA(0, 1), cA + hstepA, voffA);
;         if (wr == 1) PG8_BAR;
.LBB0_1543:
	s_setprio 0
	s_cmp_lt_i32 s80, 15
	s_cselect_b64 s[0:1], -1, 0
	s_cmp_gt_i32 s81, 14
	s_cselect_b64 s[2:3], -1, 0
	s_and_b64 s[0:1], s[0:1], s[2:3]
	s_andn2_b64 vcc, exec, s[0:1]
	s_cbranch_vccnz .LBB0_1614
	v_readfirstlane_b32 s98, v0
	s_lshr_b32 s98, s98, 8
	s_cmp_eq_u32 s98, 1
	s_cbranch_scc0 .Lsp_skip14
	s_setprio 1
.Lsp_skip14:
	v_mov_b32_e32 v12, v0
	s_cmpk_gt_i32 s96, 0xaff
	v_readfirstlane_b32 s7, v12
	s_cbranch_scc1 .LBB0_1560
	v_lshlrev_b32_e32 v1, 4, v12
	v_add_u32_e32 v2, 0x2000, v1
	s_waitcnt lgkmcnt(0)
	v_ashrrev_i32_e32 v3, 31, v2
	v_lshrrev_b32_e32 v3, 22, v3
	v_add_u32_e32 v3, v2, v3
	v_ashrrev_i32_e32 v10, 10, v3
	v_mul_i32_i24_e32 v3, 0x400, v10
	v_sub_u32_e32 v2, v2, v3
	v_lshrrev_b32_e32 v3, 4, v2
	v_bitop3_b32 v2, v3, v2, 32 bitop3:0x6c
	v_ashrrev_i32_e32 v3, 31, v2
	v_lshrrev_b32_e32 v3, 26, v3
	v_add_u32_e32 v3, v2, v3
	v_lshlrev_b32_e32 v4, 3, v10
	v_ashrrev_i32_e32 v11, 6, v3
	v_and_b32_e32 v4, -16, v4
	v_add_u32_e32 v4, v11, v4
	v_and_b32_e32 v5, 3, v11
	s_mov_b32 s4, 0x1fffe0
	v_lshrrev_b32_e32 v6, 2, v4
	v_lshlrev_b32_e32 v7, 1, v4
	v_and_b32_e32 v3, 0xc0, v3
	v_and_or_b32 v5, v4, s4, v5
	v_and_b32_e32 v6, 4, v6
	v_and_b32_e32 v7, 24, v7
	v_sub_u32_e32 v2, v2, v3
	v_mov_b32_e32 v3, 1
	v_or3_b32 v5, v5, v6, v7
	v_lshlrev_b32_e32 v6, 5, v10
	v_ashrrev_i16_sdwa v2, v3, sext(v2) dst_sel:DWORD dst_unused:UNUSED_PAD src0_sel:DWORD src1_sel:BYTE_0
	v_and_b32_e32 v6, 32, v6
	v_bfe_i32 v13, v2, 0, 16
	v_add_lshl_u32 v2, v6, v13, 1
	v_lshl_add_u32 v130, v5, 11, v2
	v_lshl_add_u32 v132, v4, 11, v2
	v_bfe_i32 v2, v12, 27, 1
	v_lshrrev_b32_e32 v2, 22, v2
	v_add_u32_e32 v2, v1, v2
	v_and_b32_e32 v2, 0xfffffc00, v2
	v_sub_u32_e32 v1, v1, v2
	v_lshrrev_b32_e32 v2, 4, v1
	v_ashrrev_i32_e32 v4, 31, v12
	v_bitop3_b32 v1, v2, v1, 32 bitop3:0x6c
	v_lshrrev_b32_e32 v4, 26, v4
	v_ashrrev_i32_e32 v2, 31, v1
	v_add_u32_e32 v4, v12, v4
	s_add_u32 s0, s78, 0xfc00000
	v_lshrrev_b32_e32 v2, 26, v2
	v_ashrrev_i32_e32 v15, 6, v4
	s_addc_u32 s1, s79, 0
	v_add_u32_e32 v2, v1, v2
	v_lshlrev_b32_e32 v4, 3, v15
	s_add_u32 s2, s78, 0x3b00000
	v_ashrrev_i32_e32 v14, 6, v2
	v_and_b32_e32 v4, -16, v4
	s_addc_u32 s3, s79, 0
	v_add_u32_e32 v4, v14, v4
	v_and_b32_e32 v5, 3, v14
	s_ashr_i32 s31, s96, 31
	v_and_or_b32 v5, v4, s4, v5
	s_lshr_b32 s4, s31, 29
	s_add_i32 s4, s96, s4
	s_ashr_i32 s10, s7, 6
	s_ashr_i32 s5, s4, 3
	s_and_b32 s4, s4, -8
	s_ashr_i32 s12, s7, 8
	s_lshl_b32 s30, s10, 10
	s_sub_i32 s4, s96, s4
	s_cmp_lt_i32 s4, 0
	s_movk_i32 s33, 0x161
	s_cselect_b32 s6, s33, 0x160
	s_mul_i32 s4, s4, s6
	s_add_i32 s4, s4, s5
	s_mul_hi_i32 s5, s4, 0x2e8ba2e9
	s_lshr_b32 s6, s5, 31
	s_ashr_i32 s5, s5, 4
	s_add_i32 s5, s5, s6
	s_lshl_b32 s8, s5, 2
	s_mulk_i32 s5, 0x58
	s_sub_i32 s4, s4, s5
	s_bfe_i32 s5, s4, 0x80000
	s_bfe_u32 s5, s5, 0x2000d
	s_add_i32 s5, s4, s5
	s_bfe_i32 s6, s5, 0x80000
	s_and_b32 s5, s5, 0xfc
	s_sub_i32 s4, s4, s5
	s_sext_i32_i16 s6, s6
	s_sext_i32_i8 s4, s4
	v_lshrrev_b32_e32 v6, 2, v4
	v_lshlrev_b32_e32 v7, 1, v4
	v_and_b32_e32 v2, 0xc0, v2
	s_lshr_b32 s6, s6, 2
	s_add_i32 s22, s8, s4
	v_and_b32_e32 v6, 4, v6
	v_and_b32_e32 v7, 24, v7
	v_sub_u32_e32 v1, v1, v2
	s_ashr_i32 s23, s22, 31
	s_bfe_i64 s[8:9], s[6:7], 0x100000
	v_or3_b32 v5, v5, v6, v7
	v_lshlrev_b32_e32 v6, 5, v15
	v_ashrrev_i16_sdwa v1, v3, sext(v1) dst_sel:DWORD dst_unused:UNUSED_PAD src0_sel:DWORD src1_sel:BYTE_0
	s_lshl_b64 s[4:5], s[22:23], 19
	s_lshl_b64 s[8:9], s[8:9], 19
	v_and_b32_e32 v6, 32, v6
	v_bfe_i32 v16, v1, 0, 16
	s_add_u32 s26, s2, s8
	v_add_lshl_u32 v1, v6, v16, 1
	s_addc_u32 s27, s3, s9
	s_add_i32 s23, s30, 0
	v_lshl_add_u32 v134, v5, 11, v1
	s_add_i32 m0, s23, 0x10000
	v_lshl_add_u32 v136, v4, 11, v1
	global_load_lds_dwordx4 v134, s[26:27]
	s_add_i32 m0, s23, 0x12000
	s_add_u32 s8, s26, 0x40000
	global_load_lds_dwordx4 v130, s[26:27]
	s_addc_u32 s9, s27, 0
	s_add_i32 m0, s23, 0x14000
	v_mov_b32_e32 v135, 0
	global_load_lds_dwordx4 v134, s[8:9]
	s_add_i32 m0, s23, 0x16000
	s_add_u32 s24, s0, s4
	s_addc_u32 s25, s1, s5
	s_add_i32 s34, s23, 0x2000
	global_load_lds_dwordx4 v130, s[8:9]
	s_mov_b32 m0, s23
	s_add_u32 s4, s24, 0x40000
	global_load_lds_dwordx4 v136, s[24:25]
	s_mov_b32 m0, s34
	s_addc_u32 s5, s25, 0
	s_add_i32 s35, s23, 0x4000
	global_load_lds_dwordx4 v132, s[24:25]
	s_mov_b32 m0, s35
	s_add_i32 s36, s23, 0x6000
	global_load_lds_dwordx4 v136, s[4:5]
	s_mov_b32 m0, s36
	v_mov_b32_e32 v131, v135
	global_load_lds_dwordx4 v132, s[4:5]
	v_mov_b32_e32 v137, v135
	v_mov_b32_e32 v133, v135
	s_cmp_eq_u32 s12, 1
	s_mov_b32 s37, 0
	v_lshl_add_u64 v[8:9], s[26:27], 0, v[134:135]
	v_lshl_add_u64 v[6:7], s[26:27], 0, v[130:131]
	v_lshl_add_u64 v[2:3], s[24:25], 0, v[136:137]
	s_cselect_b64 s[4:5], -1, 0
	s_cmp_lg_u32 s12, 1
	v_lshl_add_u64 v[4:5], s[24:25], 0, v[132:133]
	s_cbranch_scc1 .LBB0_1547
	s_barrier

.LBB0_1614:
	s_setprio 0
	s_cmp_lt_i32 s80, 16
	s_cselect_b64 s[0:1], -1, 0
	s_cmp_gt_i32 s81, 15
	s_cselect_b64 s[2:3], -1, 0
	s_and_b64 s[0:1], s[0:1], s[2:3]
	s_andn2_b64 vcc, exec, s[0:1]
	s_cbranch_vccnz .LBB0_1744
	v_readfirstlane_b32 s98, v0
	s_lshr_b32 s98, s98, 8
	s_cmp_eq_u32 s98, 1
	s_cbranch_scc0 .Lsp_skip15
	s_setprio 1

.LBB0_1744:
	s_setprio 0
	s_cmp_lt_i32 s80, 17
	s_cselect_b64 s[0:1], -1, 0
	s_cmp_gt_i32 s81, 16
	s_cselect_b64 s[2:3], -1, 0
	s_and_b64 s[0:1], s[0:1], s[2:3]
	s_andn2_b64 vcc, exec, s[0:1]
	s_cbranch_vccnz .LBB0_1841
	v_readfirstlane_b32 s98, v0
	s_lshr_b32 s98, s98, 8
	s_cmp_eq_u32 s98, 1
	s_cbranch_scc0 .Lsp_skip16
	s_setprio 1

; __device__ __forceinline__ float bflo(unsigned w) { return __uint_as_float(w << 16); }
; __device__ __forceinline__ float bfhi(unsigned w) { return __uint_as_float(w & 0xffff0000u); }
; __device__ __forceinline__ void final_norm_phase(const Frame& F, const bf16* h, const float* ssq, const float* gain, float* out) {
;     for (int it = F.bx * NTHR + F.tid; it < M * 128; it += F.G * NTHR) { const int row = it >> 7, c8 = (it & 127) * 8; const float rs = rstd_row(ssq, row);
;         const v4u w = *(const v4u*)(h + (size_t)row * DM_ + c8); const f32x4 g0 = *(const f32x4*)(gain + c8), g1 = *(const f32x4*)(gain + c8 + 4);
;         float* o = out + (size_t)row * DM_ + c8;
;         __builtin_nontemporal_store((f32x4){bflo(w.x) * rs * g0[0], bfhi(w.x) * rs * g0[1], bflo(w.y) * rs * g0[2], bfhi(w.y) * rs * g0[3]}, (f32x4*)o);
;         __builtin_nontemporal_store((f32x4){bflo(w.z) * rs * g1[0], bfhi(w.z) * rs * g1[1], bflo(w.w) * rs * g1[2], bfhi(w.w) * rs * g1[3]}, (f32x4*)(o + 4)); }
; }
.LBB0_1841:
	s_setprio 0
	s_cmp_lt_i32 s80, 18
	s_cselect_b64 s[0:1], -1, 0
	s_cmp_gt_i32 s81, 17
	s_cselect_b64 s[2:3], -1, 0
	s_and_b64 s[0:1], s[0:1], s[2:3]
	s_andn2_b64 vcc, exec, s[0:1]
	s_cbranch_vccnz .LBB0_1845
	s_mov_b32 s0, 0x400000
	v_lshl_add_u32 v2, s96, 9, v0
	s_mov_b32 s8, 28
	v_cmp_gt_i32_e32 vcc, s0, v2
	s_and_saveexec_b64 s[0:1], vcc
	s_cbranch_execz .LBB0_1845
	s_waitcnt lgkmcnt(0)
	s_add_u32 s4, s78, 0x7c00000
	s_addc_u32 s5, s79, 0
	s_add_u32 s6, s78, 0x5800000
	s_addc_u32 s7, s79, 0
	s_ashr_i32 s9, s8, 31
	s_lshl_b64 s[0:1], s[8:9], 3
	s_add_u32 s0, s74, s0
	s_addc_u32 s1, s75, s1
	s_load_dwordx2 s[0:1], s[0:1], 0x0
	v_lshlrev_b32_e32 v0, 3, v0
	s_lshl_b32 s8, s82, 9
	v_lshl_add_u32 v3, s96, 12, v0
	s_lshl_b32 s9, s82, 12
	s_mov_b64 s[2:3], 0
	v_mov_b32_e32 v4, 0x358637bd
	v_mov_b32_e32 v1, 0
	s_mov_b32 s10, 0x3fffff
